# v25 plus cross-half row max via one v_permlane32_swap instead of two ds_bpermute
# speedup vs baseline: 1.0135x; 1.0091x over previous
; __device__ __forceinline__ float a2_max(const f32x16& st0, const f32x16& st1) {
;     float mt = fmaxf(st0[0], st1[0]);
; #pragma unroll
;     for (int r = 1; r < 16; ++r) mt = fmaxf(fmaxf(mt, st0[r]), st1[r]);
;     return fmaxf(mt, __shfl_xor(mt, 32));
; }
; __device__ __forceinline__ void attn2_unit(bf16_t* Z, const bf16_t* Hb, const float* rc, const float* rs, LAS unsigned char* lds, int b, int h, int qblk) {
;     ...
;             const float mt = fmaxf(a2_max(sa0, sa1), a2_max(sb0, sb1));
;             if (kp == 0 || __builtin_amdgcn_ballot_w64(mt > 8.f) != 0ull) {
.LBB0_824:
	s_andn2_b64 vcc, exec, s[6:7]
	s_cbranch_vccnz .LBB0_833
	s_setprio 1
	v_add_u32_e32 v0, v3, v156
	ds_read_b128 v[4:7], v0
	ds_read_b128 v[8:11], v0 offset:6656
	ds_read_b128 v[12:15], v0 offset:32
	ds_read_b128 v[248:251], v0 offset:6688
	v_mov_b64_e32 v[94:95], v[62:63]
	v_mov_b64_e32 v[92:93], v[60:61]
	v_mov_b64_e32 v[90:91], v[58:59]
	v_mov_b64_e32 v[88:89], v[56:57]
	v_mov_b64_e32 v[86:87], v[54:55]
	v_mov_b64_e32 v[84:85], v[52:53]
	v_mov_b64_e32 v[82:83], v[50:51]
	v_mov_b64_e32 v[80:81], v[48:49]
	s_waitcnt lgkmcnt(3)
	v_mfma_f32_32x32x16_bf16 v[112:127], v[4:7], v[128:131], v[48:63]
	ds_read_b128 v[252:255], v0 offset:64
	s_waitcnt lgkmcnt(3)
	v_mfma_f32_32x32x16_bf16 v[96:111], v[8:11], v[128:131], v[48:63]
	ds_read_b128 v[4:7], v0 offset:6720
	s_waitcnt lgkmcnt(3)
	v_mfma_f32_32x32x16_bf16 v[112:127], v[12:15], v[132:135], v[112:127]
	ds_read_b128 v[8:11], v0 offset:96
	s_waitcnt lgkmcnt(3)
	v_mfma_f32_32x32x16_bf16 v[96:111], v[248:251], v[132:135], v[96:111]
	ds_read_b128 v[12:15], v0 offset:6752
	s_waitcnt lgkmcnt(3)
	v_mfma_f32_32x32x16_bf16 v[112:127], v[252:255], v[136:139], v[112:127]
	ds_read_b128 v[248:251], v0 offset:128
	s_waitcnt lgkmcnt(3)
	v_mfma_f32_32x32x16_bf16 v[96:111], v[4:7], v[136:139], v[96:111]
	ds_read_b128 v[252:255], v0 offset:6784
	s_waitcnt lgkmcnt(3)
	v_mfma_f32_32x32x16_bf16 v[112:127], v[8:11], v[140:143], v[112:127]
	ds_read_b128 v[4:7], v0 offset:160
	s_waitcnt lgkmcnt(3)
	v_mfma_f32_32x32x16_bf16 v[96:111], v[12:15], v[140:143], v[96:111]
	ds_read_b128 v[8:11], v0 offset:13312
	s_waitcnt lgkmcnt(3)
	v_mfma_f32_32x32x16_bf16 v[112:127], v[248:251], v[144:147], v[112:127]
	ds_read_b128 v[12:15], v0 offset:6816
	s_waitcnt lgkmcnt(3)
	v_mfma_f32_32x32x16_bf16 v[96:111], v[252:255], v[144:147], v[96:111]
	ds_read_b128 v[248:251], v0 offset:19968
	s_waitcnt lgkmcnt(3)
	v_mfma_f32_32x32x16_bf16 v[112:127], v[4:7], v[148:151], v[112:127]
	ds_read_b128 v[252:255], v0 offset:13344
	s_waitcnt lgkmcnt(3)
	v_mfma_f32_32x32x16_bf16 v[64:79], v[8:11], v[128:131], v[48:63]
	ds_read_b128 v[4:7], v0 offset:20000
	s_waitcnt lgkmcnt(3)
	v_mfma_f32_32x32x16_bf16 v[96:111], v[12:15], v[148:151], v[96:111]
	ds_read_b128 v[8:11], v0 offset:13376
	s_waitcnt lgkmcnt(3)
	v_mfma_f32_32x32x16_bf16 v[80:95], v[248:251], v[128:131], v[80:95]
	ds_read_b128 v[12:15], v0 offset:20032
	s_waitcnt lgkmcnt(3)
	v_mfma_f32_32x32x16_bf16 v[64:79], v[252:255], v[132:135], v[64:79]
	ds_read_b128 v[248:251], v0 offset:13408
	s_waitcnt lgkmcnt(3)
	v_mfma_f32_32x32x16_bf16 v[80:95], v[4:7], v[132:135], v[80:95]
	ds_read_b128 v[252:255], v0 offset:20064
	s_waitcnt lgkmcnt(3)
	v_mfma_f32_32x32x16_bf16 v[64:79], v[8:11], v[136:139], v[64:79]
	ds_read_b128 v[4:7], v0 offset:13440
	s_waitcnt lgkmcnt(3)
	v_mfma_f32_32x32x16_bf16 v[80:95], v[12:15], v[136:139], v[80:95]
	ds_read_b128 v[8:11], v0 offset:20096
	s_waitcnt lgkmcnt(3)
	v_mfma_f32_32x32x16_bf16 v[64:79], v[248:251], v[140:143], v[64:79]
	ds_read_b128 v[12:15], v0 offset:13472
	s_waitcnt lgkmcnt(3)
	v_mfma_f32_32x32x16_bf16 v[80:95], v[252:255], v[140:143], v[80:95]
	ds_read_b128 v[248:251], v0 offset:20128
	s_waitcnt lgkmcnt(3)
	v_mfma_f32_32x32x16_bf16 v[64:79], v[4:7], v[144:147], v[64:79]
	s_waitcnt lgkmcnt(2)
	v_mfma_f32_32x32x16_bf16 v[80:95], v[8:11], v[144:147], v[80:95]
	s_waitcnt lgkmcnt(1)
	v_mfma_f32_32x32x16_bf16 v[64:79], v[12:15], v[148:151], v[64:79]
	s_waitcnt lgkmcnt(0)
	v_mfma_f32_32x32x16_bf16 v[80:95], v[248:251], v[148:151], v[80:95]
	s_setprio 0
	v_max_f32_e32 v0, v96, v96
	v_max_f32_e32 v3, v112, v112
	v_max_f32_e32 v0, v3, v0
	s_nop 7
	v_max_f32_e32 v3, v80, v80
	v_max_f32_e32 v4, v64, v64
	v_max_f32_e32 v3, v4, v3
	v_max3_f32 v3, v3, v65, v81
	v_max3_f32 v3, v3, v66, v82
	v_max3_f32 v0, v0, v113, v97
	v_max3_f32 v3, v3, v67, v83
	v_max3_f32 v0, v0, v114, v98
	v_max3_f32 v3, v3, v68, v84
	v_max3_f32 v0, v0, v115, v99
	v_max3_f32 v3, v3, v69, v85
	v_max3_f32 v0, v0, v116, v100
	v_max3_f32 v3, v3, v70, v86
	v_max3_f32 v0, v0, v117, v101
	v_max3_f32 v3, v3, v71, v87
	v_max3_f32 v0, v0, v118, v102
	v_max3_f32 v3, v3, v72, v88
	v_max3_f32 v0, v0, v119, v103
	v_max3_f32 v3, v3, v73, v89
	v_max3_f32 v0, v0, v120, v104
	v_max3_f32 v3, v3, v74, v90
	v_max3_f32 v0, v0, v121, v105
	v_max3_f32 v3, v3, v75, v91
	v_max3_f32 v0, v0, v122, v106
	v_max3_f32 v3, v3, v76, v92
	v_max3_f32 v0, v0, v123, v107
	v_max3_f32 v3, v3, v77, v93
	v_max3_f32 v0, v0, v124, v108
	v_max3_f32 v3, v3, v78, v94
	v_max3_f32 v3, v3, v79, v95
	v_max3_f32 v0, v0, v125, v109
	v_max3_f32 v0, v0, v126, v110
	v_max3_f32 v0, v0, v127, v111
	s_cmp_eq_u32 s65, 1
	v_max_f32_e32 v3, v3, v0
	v_mov_b32_e32 v4, v3
	v_mov_b32_e32 v5, v3
	s_cselect_b64 s[34:35], -1, 0
	s_cmp_lg_u32 s65, 1
	v_permlane32_swap_b32_e32 v4, v5
	v_max_f32_e32 v3, v4, v5
	s_cbranch_scc0 .LBB0_835
	v_cmp_lt_f32_e32 vcc, s53, v3
	s_mov_b64 s[24:25], 0
	s_mov_b64 s[6:7], 0
	s_cbranch_vccz .LBB0_828
	v_max_f32_e32 v0, v3, v3
	v_max_f32_e32 v0, 0, v0
	s_mov_b64 s[6:7], -1

; __device__ __forceinline__ float a2_max(const f32x16& st0, const f32x16& st1) {
;     float mt = fmaxf(st0[0], st1[0]);
; #pragma unroll
;     for (int r = 1; r < 16; ++r) mt = fmaxf(fmaxf(mt, st0[r]), st1[r]);
;     return fmaxf(mt, __shfl_xor(mt, 32));
; }
; __device__ __forceinline__ void attn2_unit(bf16_t* Z, const bf16_t* Hb, const float* rc, const float* rs, LAS unsigned char* lds, int b, int h, int qblk) {
;     ...
;             const float mt = fmaxf(a2_max(sa0, sa1), a2_max(sb0, sb1));
;             if (kp == 0 || __builtin_amdgcn_ballot_w64(mt > 8.f) != 0ull) {
.LBB0_870:
	s_andn2_b64 vcc, exec, s[6:7]
	s_cbranch_vccnz .LBB0_879
	s_setprio 1
	v_add_u32_e32 v0, v3, v156
	ds_read_b128 v[4:7], v0
	ds_read_b128 v[8:11], v0 offset:6656
	ds_read_b128 v[12:15], v0 offset:32
	ds_read_b128 v[248:251], v0 offset:6688
	v_mov_b64_e32 v[94:95], v[62:63]
	v_mov_b64_e32 v[92:93], v[60:61]
	v_mov_b64_e32 v[90:91], v[58:59]
	v_mov_b64_e32 v[88:89], v[56:57]
	v_mov_b64_e32 v[86:87], v[54:55]
	v_mov_b64_e32 v[84:85], v[52:53]
	v_mov_b64_e32 v[82:83], v[50:51]
	v_mov_b64_e32 v[80:81], v[48:49]
	s_waitcnt lgkmcnt(3)
	v_mfma_f32_32x32x16_bf16 v[112:127], v[4:7], v[128:131], v[48:63]
	ds_read_b128 v[252:255], v0 offset:64
	s_waitcnt lgkmcnt(3)
	v_mfma_f32_32x32x16_bf16 v[96:111], v[8:11], v[128:131], v[48:63]
	ds_read_b128 v[4:7], v0 offset:6720
	s_waitcnt lgkmcnt(3)
	v_mfma_f32_32x32x16_bf16 v[112:127], v[12:15], v[132:135], v[112:127]
	ds_read_b128 v[8:11], v0 offset:96
	s_waitcnt lgkmcnt(3)
	v_mfma_f32_32x32x16_bf16 v[96:111], v[248:251], v[132:135], v[96:111]
	ds_read_b128 v[12:15], v0 offset:6752
	s_waitcnt lgkmcnt(3)
	v_mfma_f32_32x32x16_bf16 v[112:127], v[252:255], v[136:139], v[112:127]
	ds_read_b128 v[248:251], v0 offset:128
	s_waitcnt lgkmcnt(3)
	v_mfma_f32_32x32x16_bf16 v[96:111], v[4:7], v[136:139], v[96:111]
	ds_read_b128 v[252:255], v0 offset:6784
	s_waitcnt lgkmcnt(3)
	v_mfma_f32_32x32x16_bf16 v[112:127], v[8:11], v[140:143], v[112:127]
	ds_read_b128 v[4:7], v0 offset:160
	s_waitcnt lgkmcnt(3)
	v_mfma_f32_32x32x16_bf16 v[96:111], v[12:15], v[140:143], v[96:111]
	ds_read_b128 v[8:11], v0 offset:13312
	s_waitcnt lgkmcnt(3)
	v_mfma_f32_32x32x16_bf16 v[112:127], v[248:251], v[144:147], v[112:127]
	ds_read_b128 v[12:15], v0 offset:6816
	s_waitcnt lgkmcnt(3)
	v_mfma_f32_32x32x16_bf16 v[96:111], v[252:255], v[144:147], v[96:111]
	ds_read_b128 v[248:251], v0 offset:19968
	s_waitcnt lgkmcnt(3)
	v_mfma_f32_32x32x16_bf16 v[112:127], v[4:7], v[148:151], v[112:127]
	ds_read_b128 v[252:255], v0 offset:13344
	s_waitcnt lgkmcnt(3)
	v_mfma_f32_32x32x16_bf16 v[64:79], v[8:11], v[128:131], v[48:63]
	ds_read_b128 v[4:7], v0 offset:20000
	s_waitcnt lgkmcnt(3)
	v_mfma_f32_32x32x16_bf16 v[96:111], v[12:15], v[148:151], v[96:111]
	ds_read_b128 v[8:11], v0 offset:13376
	s_waitcnt lgkmcnt(3)
	v_mfma_f32_32x32x16_bf16 v[80:95], v[248:251], v[128:131], v[80:95]
	ds_read_b128 v[12:15], v0 offset:20032
	s_waitcnt lgkmcnt(3)
	v_mfma_f32_32x32x16_bf16 v[64:79], v[252:255], v[132:135], v[64:79]
	ds_read_b128 v[248:251], v0 offset:13408
	s_waitcnt lgkmcnt(3)
	v_mfma_f32_32x32x16_bf16 v[80:95], v[4:7], v[132:135], v[80:95]
	ds_read_b128 v[252:255], v0 offset:20064
	s_waitcnt lgkmcnt(3)
	v_mfma_f32_32x32x16_bf16 v[64:79], v[8:11], v[136:139], v[64:79]
	ds_read_b128 v[4:7], v0 offset:13440
	s_waitcnt lgkmcnt(3)
	v_mfma_f32_32x32x16_bf16 v[80:95], v[12:15], v[136:139], v[80:95]
	ds_read_b128 v[8:11], v0 offset:20096
	s_waitcnt lgkmcnt(3)
	v_mfma_f32_32x32x16_bf16 v[64:79], v[248:251], v[140:143], v[64:79]
	ds_read_b128 v[12:15], v0 offset:13472
	s_waitcnt lgkmcnt(3)
	v_mfma_f32_32x32x16_bf16 v[80:95], v[252:255], v[140:143], v[80:95]
	ds_read_b128 v[248:251], v0 offset:20128
	s_waitcnt lgkmcnt(3)
	v_mfma_f32_32x32x16_bf16 v[64:79], v[4:7], v[144:147], v[64:79]
	s_waitcnt lgkmcnt(2)
	v_mfma_f32_32x32x16_bf16 v[80:95], v[8:11], v[144:147], v[80:95]
	s_waitcnt lgkmcnt(1)
	v_mfma_f32_32x32x16_bf16 v[64:79], v[12:15], v[148:151], v[64:79]
	s_waitcnt lgkmcnt(0)
	v_mfma_f32_32x32x16_bf16 v[80:95], v[248:251], v[148:151], v[80:95]
	s_setprio 0
	v_max_f32_e32 v0, v96, v96
	v_max_f32_e32 v3, v112, v112
	v_max_f32_e32 v0, v3, v0
	s_nop 7
	v_max_f32_e32 v3, v80, v80
	v_max_f32_e32 v4, v64, v64
	v_max_f32_e32 v3, v4, v3
	v_max3_f32 v3, v3, v65, v81
	v_max3_f32 v3, v3, v66, v82
	v_max3_f32 v0, v0, v113, v97
	v_max3_f32 v3, v3, v67, v83
	v_max3_f32 v0, v0, v114, v98
	v_max3_f32 v3, v3, v68, v84
	v_max3_f32 v0, v0, v115, v99
	v_max3_f32 v3, v3, v69, v85
	v_max3_f32 v0, v0, v116, v100
	v_max3_f32 v3, v3, v70, v86
	v_max3_f32 v0, v0, v117, v101
	v_max3_f32 v3, v3, v71, v87
	v_max3_f32 v0, v0, v118, v102
	v_max3_f32 v3, v3, v72, v88
	v_max3_f32 v0, v0, v119, v103
	v_max3_f32 v3, v3, v73, v89
	v_max3_f32 v0, v0, v120, v104
	v_max3_f32 v3, v3, v74, v90
	v_max3_f32 v0, v0, v121, v105
	v_max3_f32 v3, v3, v75, v91
	v_max3_f32 v0, v0, v122, v106
	v_max3_f32 v3, v3, v76, v92
	v_max3_f32 v0, v0, v123, v107
	v_max3_f32 v3, v3, v77, v93
	v_max3_f32 v0, v0, v124, v108
	v_max3_f32 v3, v3, v78, v94
	v_max3_f32 v3, v3, v79, v95
	v_max3_f32 v0, v0, v125, v109
	v_max3_f32 v0, v0, v126, v110
	v_max3_f32 v0, v0, v127, v111
	s_cmp_eq_u32 s35, 1
	v_max_f32_e32 v3, v3, v0
	v_mov_b32_e32 v4, v3
	v_mov_b32_e32 v5, v3
	s_cselect_b64 s[28:29], -1, 0
	s_cmp_lg_u32 s35, 1
	v_permlane32_swap_b32_e32 v4, v5
	v_max_f32_e32 v3, v4, v5
	s_cbranch_scc0 .LBB0_881
	v_cmp_lt_f32_e32 vcc, s53, v3
	s_mov_b64 s[24:25], 0
	s_mov_b64 s[6:7], 0
	s_cbranch_vccz .LBB0_874
	v_max_f32_e32 v0, v3, v3
	v_max_f32_e32 v0, 0, v0
	s_mov_b64 s[6:7], -1

; __device__ __forceinline__ float a2_max(const f32x16& st0, const f32x16& st1) {
;     float mt = fmaxf(st0[0], st1[0]);
; #pragma unroll
;     for (int r = 1; r < 16; ++r) mt = fmaxf(fmaxf(mt, st0[r]), st1[r]);
;     return fmaxf(mt, __shfl_xor(mt, 32));
; }
; __device__ __forceinline__ void attn2_unit(bf16_t* Z, const bf16_t* Hb, const float* rc, const float* rs, LAS unsigned char* lds, int b, int h, int qblk) {
;     ...
;             const float mt = fmaxf(a2_max(sa0, sa1), a2_max(sb0, sb1));
;             if (kp == 0 || __builtin_amdgcn_ballot_w64(mt > 8.f) != 0ull) {
.LBB0_2235:
	s_andn2_b64 vcc, exec, s[6:7]
	s_cbranch_vccnz .LBB0_2244
	s_setprio 1
	v_add_u32_e32 v0, v3, v156
	ds_read_b128 v[4:7], v0
	ds_read_b128 v[8:11], v0 offset:6656
	ds_read_b128 v[12:15], v0 offset:32
	ds_read_b128 v[248:251], v0 offset:6688
	v_mov_b64_e32 v[94:95], v[62:63]
	v_mov_b64_e32 v[92:93], v[60:61]
	v_mov_b64_e32 v[90:91], v[58:59]
	v_mov_b64_e32 v[88:89], v[56:57]
	v_mov_b64_e32 v[86:87], v[54:55]
	v_mov_b64_e32 v[84:85], v[52:53]
	v_mov_b64_e32 v[82:83], v[50:51]
	v_mov_b64_e32 v[80:81], v[48:49]
	s_waitcnt lgkmcnt(3)
	v_mfma_f32_32x32x16_bf16 v[112:127], v[4:7], v[128:131], v[48:63]
	ds_read_b128 v[252:255], v0 offset:64
	s_waitcnt lgkmcnt(3)
	v_mfma_f32_32x32x16_bf16 v[96:111], v[8:11], v[128:131], v[48:63]
	ds_read_b128 v[4:7], v0 offset:6720
	s_waitcnt lgkmcnt(3)
	v_mfma_f32_32x32x16_bf16 v[112:127], v[12:15], v[132:135], v[112:127]
	ds_read_b128 v[8:11], v0 offset:96
	s_waitcnt lgkmcnt(3)
	v_mfma_f32_32x32x16_bf16 v[96:111], v[248:251], v[132:135], v[96:111]
	ds_read_b128 v[12:15], v0 offset:6752
	s_waitcnt lgkmcnt(3)
	v_mfma_f32_32x32x16_bf16 v[112:127], v[252:255], v[136:139], v[112:127]
	ds_read_b128 v[248:251], v0 offset:128
	s_waitcnt lgkmcnt(3)
	v_mfma_f32_32x32x16_bf16 v[96:111], v[4:7], v[136:139], v[96:111]
	ds_read_b128 v[252:255], v0 offset:6784
	s_waitcnt lgkmcnt(3)
	v_mfma_f32_32x32x16_bf16 v[112:127], v[8:11], v[140:143], v[112:127]
	ds_read_b128 v[4:7], v0 offset:160
	s_waitcnt lgkmcnt(3)
	v_mfma_f32_32x32x16_bf16 v[96:111], v[12:15], v[140:143], v[96:111]
	ds_read_b128 v[8:11], v0 offset:13312
	s_waitcnt lgkmcnt(3)
	v_mfma_f32_32x32x16_bf16 v[112:127], v[248:251], v[144:147], v[112:127]
	ds_read_b128 v[12:15], v0 offset:6816
	s_waitcnt lgkmcnt(3)
	v_mfma_f32_32x32x16_bf16 v[96:111], v[252:255], v[144:147], v[96:111]
	ds_read_b128 v[248:251], v0 offset:19968
	s_waitcnt lgkmcnt(3)
	v_mfma_f32_32x32x16_bf16 v[112:127], v[4:7], v[148:151], v[112:127]
	ds_read_b128 v[252:255], v0 offset:13344
	s_waitcnt lgkmcnt(3)
	v_mfma_f32_32x32x16_bf16 v[64:79], v[8:11], v[128:131], v[48:63]
	ds_read_b128 v[4:7], v0 offset:20000
	s_waitcnt lgkmcnt(3)
	v_mfma_f32_32x32x16_bf16 v[96:111], v[12:15], v[148:151], v[96:111]
	ds_read_b128 v[8:11], v0 offset:13376
	s_waitcnt lgkmcnt(3)
	v_mfma_f32_32x32x16_bf16 v[80:95], v[248:251], v[128:131], v[80:95]
	ds_read_b128 v[12:15], v0 offset:20032
	s_waitcnt lgkmcnt(3)
	v_mfma_f32_32x32x16_bf16 v[64:79], v[252:255], v[132:135], v[64:79]
	ds_read_b128 v[248:251], v0 offset:13408
	s_waitcnt lgkmcnt(3)
	v_mfma_f32_32x32x16_bf16 v[80:95], v[4:7], v[132:135], v[80:95]
	ds_read_b128 v[252:255], v0 offset:20064
	s_waitcnt lgkmcnt(3)
	v_mfma_f32_32x32x16_bf16 v[64:79], v[8:11], v[136:139], v[64:79]
	ds_read_b128 v[4:7], v0 offset:13440
	s_waitcnt lgkmcnt(3)
	v_mfma_f32_32x32x16_bf16 v[80:95], v[12:15], v[136:139], v[80:95]
	ds_read_b128 v[8:11], v0 offset:20096
	s_waitcnt lgkmcnt(3)
	v_mfma_f32_32x32x16_bf16 v[64:79], v[248:251], v[140:143], v[64:79]
	ds_read_b128 v[12:15], v0 offset:13472
	s_waitcnt lgkmcnt(3)
	v_mfma_f32_32x32x16_bf16 v[80:95], v[252:255], v[140:143], v[80:95]
	ds_read_b128 v[248:251], v0 offset:20128
	s_waitcnt lgkmcnt(3)
	v_mfma_f32_32x32x16_bf16 v[64:79], v[4:7], v[144:147], v[64:79]
	s_waitcnt lgkmcnt(2)
	v_mfma_f32_32x32x16_bf16 v[80:95], v[8:11], v[144:147], v[80:95]
	s_waitcnt lgkmcnt(1)
	v_mfma_f32_32x32x16_bf16 v[64:79], v[12:15], v[148:151], v[64:79]
	s_waitcnt lgkmcnt(0)
	v_mfma_f32_32x32x16_bf16 v[80:95], v[248:251], v[148:151], v[80:95]
	s_setprio 0
	v_max_f32_e32 v0, v96, v96
	v_max_f32_e32 v3, v112, v112
	v_max_f32_e32 v0, v3, v0
	s_nop 7
	v_max_f32_e32 v3, v80, v80
	v_max_f32_e32 v4, v64, v64
	v_max_f32_e32 v3, v4, v3
	v_max3_f32 v3, v3, v65, v81
	v_max3_f32 v3, v3, v66, v82
	v_max3_f32 v0, v0, v113, v97
	v_max3_f32 v3, v3, v67, v83
	v_max3_f32 v0, v0, v114, v98
	v_max3_f32 v3, v3, v68, v84
	v_max3_f32 v0, v0, v115, v99
	v_max3_f32 v3, v3, v69, v85
	v_max3_f32 v0, v0, v116, v100
	v_max3_f32 v3, v3, v70, v86
	v_max3_f32 v0, v0, v117, v101
	v_max3_f32 v3, v3, v71, v87
	v_max3_f32 v0, v0, v118, v102
	v_max3_f32 v3, v3, v72, v88
	v_max3_f32 v0, v0, v119, v103
	v_max3_f32 v3, v3, v73, v89
	v_max3_f32 v0, v0, v120, v104
	v_max3_f32 v3, v3, v74, v90
	v_max3_f32 v0, v0, v121, v105
	v_max3_f32 v3, v3, v75, v91
	v_max3_f32 v0, v0, v122, v106
	v_max3_f32 v3, v3, v76, v92
	v_max3_f32 v0, v0, v123, v107
	v_max3_f32 v3, v3, v77, v93
	v_max3_f32 v0, v0, v124, v108
	v_max3_f32 v3, v3, v78, v94
	v_max3_f32 v3, v3, v79, v95
	v_max3_f32 v0, v0, v125, v109
	v_max3_f32 v0, v0, v126, v110
	v_max3_f32 v0, v0, v127, v111
	s_cmp_eq_u32 s47, 1
	v_max_f32_e32 v3, v3, v0
	v_mov_b32_e32 v4, v3
	v_mov_b32_e32 v5, v3
	s_cselect_b64 s[30:31], -1, 0
	s_cmp_lg_u32 s47, 1
	v_permlane32_swap_b32_e32 v4, v5
	v_max_f32_e32 v3, v4, v5
	s_cbranch_scc0 .LBB0_2246
	v_cmp_lt_f32_e32 vcc, s41, v3
	s_mov_b64 s[24:25], 0
	s_mov_b64 s[6:7], 0
	s_cbranch_vccz .LBB0_2239
	v_max_f32_e32 v0, v3, v3
	v_max_f32_e32 v0, 0, v0
	s_mov_b64 s[6:7], -1

; __device__ __forceinline__ float a2_max(const f32x16& st0, const f32x16& st1) {
;     float mt = fmaxf(st0[0], st1[0]);
; #pragma unroll
;     for (int r = 1; r < 16; ++r) mt = fmaxf(fmaxf(mt, st0[r]), st1[r]);
;     return fmaxf(mt, __shfl_xor(mt, 32));
; }
; __device__ __forceinline__ void attn2_unit(bf16_t* Z, const bf16_t* Hb, const float* rc, const float* rs, LAS unsigned char* lds, int b, int h, int qblk) {
;     ...
;             const float mt = fmaxf(a2_max(sa0, sa1), a2_max(sb0, sb1));
;             if (kp == 0 || __builtin_amdgcn_ballot_w64(mt > 8.f) != 0ull) {
.LBB0_2281:
	s_andn2_b64 vcc, exec, s[6:7]
	s_cbranch_vccnz .LBB0_2290
	s_setprio 1
	v_add_u32_e32 v0, v3, v156
	ds_read_b128 v[4:7], v0
	ds_read_b128 v[8:11], v0 offset:6656
	ds_read_b128 v[12:15], v0 offset:32
	ds_read_b128 v[248:251], v0 offset:6688
	v_mov_b64_e32 v[94:95], v[62:63]
	v_mov_b64_e32 v[92:93], v[60:61]
	v_mov_b64_e32 v[90:91], v[58:59]
	v_mov_b64_e32 v[88:89], v[56:57]
	v_mov_b64_e32 v[86:87], v[54:55]
	v_mov_b64_e32 v[84:85], v[52:53]
	v_mov_b64_e32 v[82:83], v[50:51]
	v_mov_b64_e32 v[80:81], v[48:49]
	s_waitcnt lgkmcnt(3)
	v_mfma_f32_32x32x16_bf16 v[112:127], v[4:7], v[128:131], v[48:63]
	ds_read_b128 v[252:255], v0 offset:64
	s_waitcnt lgkmcnt(3)
	v_mfma_f32_32x32x16_bf16 v[96:111], v[8:11], v[128:131], v[48:63]
	ds_read_b128 v[4:7], v0 offset:6720
	s_waitcnt lgkmcnt(3)
	v_mfma_f32_32x32x16_bf16 v[112:127], v[12:15], v[132:135], v[112:127]
	ds_read_b128 v[8:11], v0 offset:96
	s_waitcnt lgkmcnt(3)
	v_mfma_f32_32x32x16_bf16 v[96:111], v[248:251], v[132:135], v[96:111]
	ds_read_b128 v[12:15], v0 offset:6752
	s_waitcnt lgkmcnt(3)
	v_mfma_f32_32x32x16_bf16 v[112:127], v[252:255], v[136:139], v[112:127]
	ds_read_b128 v[248:251], v0 offset:128
	s_waitcnt lgkmcnt(3)
	v_mfma_f32_32x32x16_bf16 v[96:111], v[4:7], v[136:139], v[96:111]
	ds_read_b128 v[252:255], v0 offset:6784
	s_waitcnt lgkmcnt(3)
	v_mfma_f32_32x32x16_bf16 v[112:127], v[8:11], v[140:143], v[112:127]
	ds_read_b128 v[4:7], v0 offset:160
	s_waitcnt lgkmcnt(3)
	v_mfma_f32_32x32x16_bf16 v[96:111], v[12:15], v[140:143], v[96:111]
	ds_read_b128 v[8:11], v0 offset:13312
	s_waitcnt lgkmcnt(3)
	v_mfma_f32_32x32x16_bf16 v[112:127], v[248:251], v[144:147], v[112:127]
	ds_read_b128 v[12:15], v0 offset:6816
	s_waitcnt lgkmcnt(3)
	v_mfma_f32_32x32x16_bf16 v[96:111], v[252:255], v[144:147], v[96:111]
	ds_read_b128 v[248:251], v0 offset:19968
	s_waitcnt lgkmcnt(3)
	v_mfma_f32_32x32x16_bf16 v[112:127], v[4:7], v[148:151], v[112:127]
	ds_read_b128 v[252:255], v0 offset:13344
	s_waitcnt lgkmcnt(3)
	v_mfma_f32_32x32x16_bf16 v[64:79], v[8:11], v[128:131], v[48:63]
	ds_read_b128 v[4:7], v0 offset:20000
	s_waitcnt lgkmcnt(3)
	v_mfma_f32_32x32x16_bf16 v[96:111], v[12:15], v[148:151], v[96:111]
	ds_read_b128 v[8:11], v0 offset:13376
	s_waitcnt lgkmcnt(3)
	v_mfma_f32_32x32x16_bf16 v[80:95], v[248:251], v[128:131], v[80:95]
	ds_read_b128 v[12:15], v0 offset:20032
	s_waitcnt lgkmcnt(3)
	v_mfma_f32_32x32x16_bf16 v[64:79], v[252:255], v[132:135], v[64:79]
	ds_read_b128 v[248:251], v0 offset:13408
	s_waitcnt lgkmcnt(3)
	v_mfma_f32_32x32x16_bf16 v[80:95], v[4:7], v[132:135], v[80:95]
	ds_read_b128 v[252:255], v0 offset:20064
	s_waitcnt lgkmcnt(3)
	v_mfma_f32_32x32x16_bf16 v[64:79], v[8:11], v[136:139], v[64:79]
	ds_read_b128 v[4:7], v0 offset:13440
	s_waitcnt lgkmcnt(3)
	v_mfma_f32_32x32x16_bf16 v[80:95], v[12:15], v[136:139], v[80:95]
	ds_read_b128 v[8:11], v0 offset:20096
	s_waitcnt lgkmcnt(3)
	v_mfma_f32_32x32x16_bf16 v[64:79], v[248:251], v[140:143], v[64:79]
	ds_read_b128 v[12:15], v0 offset:13472
	s_waitcnt lgkmcnt(3)
	v_mfma_f32_32x32x16_bf16 v[80:95], v[252:255], v[140:143], v[80:95]
	ds_read_b128 v[248:251], v0 offset:20128
	s_waitcnt lgkmcnt(3)
	v_mfma_f32_32x32x16_bf16 v[64:79], v[4:7], v[144:147], v[64:79]
	s_waitcnt lgkmcnt(2)
	v_mfma_f32_32x32x16_bf16 v[80:95], v[8:11], v[144:147], v[80:95]
	s_waitcnt lgkmcnt(1)
	v_mfma_f32_32x32x16_bf16 v[64:79], v[12:15], v[148:151], v[64:79]
	s_waitcnt lgkmcnt(0)
	v_mfma_f32_32x32x16_bf16 v[80:95], v[248:251], v[148:151], v[80:95]
	s_setprio 0
	v_max_f32_e32 v0, v96, v96
	v_max_f32_e32 v3, v112, v112
	v_max_f32_e32 v0, v3, v0
	s_nop 7
	v_max_f32_e32 v3, v80, v80
	v_max_f32_e32 v4, v64, v64
	v_max_f32_e32 v3, v4, v3
	v_max3_f32 v3, v3, v65, v81
	v_max3_f32 v3, v3, v66, v82
	v_max3_f32 v0, v0, v113, v97
	v_max3_f32 v3, v3, v67, v83
	v_max3_f32 v0, v0, v114, v98
	v_max3_f32 v3, v3, v68, v84
	v_max3_f32 v0, v0, v115, v99
	v_max3_f32 v3, v3, v69, v85
	v_max3_f32 v0, v0, v116, v100
	v_max3_f32 v3, v3, v70, v86
	v_max3_f32 v0, v0, v117, v101
	v_max3_f32 v3, v3, v71, v87
	v_max3_f32 v0, v0, v118, v102
	v_max3_f32 v3, v3, v72, v88
	v_max3_f32 v0, v0, v119, v103
	v_max3_f32 v3, v3, v73, v89
	v_max3_f32 v0, v0, v120, v104
	v_max3_f32 v3, v3, v74, v90
	v_max3_f32 v0, v0, v121, v105
	v_max3_f32 v3, v3, v75, v91
	v_max3_f32 v0, v0, v122, v106
	v_max3_f32 v3, v3, v76, v92
	v_max3_f32 v0, v0, v123, v107
	v_max3_f32 v3, v3, v77, v93
	v_max3_f32 v0, v0, v124, v108
	v_max3_f32 v3, v3, v78, v94
	v_max3_f32 v3, v3, v79, v95
	v_max3_f32 v0, v0, v125, v109
	v_max3_f32 v0, v0, v126, v110
	v_max3_f32 v0, v0, v127, v111
	s_cmp_eq_u32 s31, 1
	v_max_f32_e32 v3, v3, v0
	v_mov_b32_e32 v4, v3
	v_mov_b32_e32 v5, v3
	s_cselect_b64 s[26:27], -1, 0
	s_cmp_lg_u32 s31, 1
	v_permlane32_swap_b32_e32 v4, v5
	v_max_f32_e32 v3, v4, v5
	s_cbranch_scc0 .LBB0_2292
	v_cmp_lt_f32_e32 vcc, s41, v3
	s_mov_b64 s[24:25], 0
	s_mov_b64 s[6:7], 0
	s_cbranch_vccz .LBB0_2285
	v_max_f32_e32 v0, v3, v3
	v_max_f32_e32 v0, 0, v0
	s_mov_b64 s[6:7], -1
